# attention: waves 4,5 skip the last key tile QK/softmax (wholly above their rows) and finish with one PV of the previous tile
# speedup vs baseline: 1.0017x; 1.0017x over previous
; #define SBAR() __builtin_amdgcn_sched_barrier(0)
; #define RESC() do { if (resc) { asm volatile("s_waitcnt lgkmcnt(0)" ::: "memory"); \
;       _Pragma("unroll") for (int d_ = 0; d_ < 2; ++d_) _Pragma("unroll") for (int r = 0; r < 16; ++r) o[d_][r] *= wsf[crow(r, hi)]; } } while (0)
; #define PKW(P, B) pkh(P[B], P[B + 1])
; template <int THRL> __device__ __forceinline__ void attn_unit(int b, int h, int qb, const f16_t* Q, const f16_t* __restrict__ K, const f16_t* __restrict__ V, f16_t* O, const float* __restrict__ kms, char* shm) {
;     ...
;     STEP(pB0, pB1, pA0, pA1, NT - 1, false, false, false); RESC();
;     { float sacc = pB0[0] + pB0[1]; _Pragma("unroll") for (int r = 2; r < 16; ++r) sacc += pB0[r]; _Pragma("unroll") for (int r = 0; r < 16; ++r) sacc += pB1[r]; l_reg += sacc;
;       pw0 = (u32x4){PKW(pB0, 0), PKW(pB0, 2), PKW(pB0, 4), PKW(pB0, 6)}; pw1 = (u32x4){PKW(pB0, 8), PKW(pB0, 10), PKW(pB0, 12), PKW(pB0, 14)}; pw2 = (u32x4){PKW(pB1, 0), PKW(pB1, 2), PKW(pB1, 4), PKW(pB1, 6)}; pw3 = (u32x4){PKW(pB1, 8), PKW(pB1, 10), PKW(pB1, 12), PKW(pB1, 14)};
;       SBAR(); pv(o, vb0 + sl_cur, PAF(0), PAF(1), PAF(2), PAF(3)); }
.Lattn_fin_full:
	s_cmp_gt_u32 s29, 5
	s_cbranch_scc1 .Lattn_fin_full67
	v_mov_b64_e32 v[82:83], v[66:67]
	v_mov_b64_e32 v[84:85], v[68:69]
	v_mov_b64_e32 v[86:87], v[70:71]
	v_mov_b64_e32 v[88:89], v[72:73]
	v_mov_b64_e32 v[90:91], v[74:75]
	v_mov_b64_e32 v[92:93], v[76:77]
	v_mov_b64_e32 v[94:95], v[78:79]
	v_mov_b64_e32 v[96:97], v[80:81]
	v_mov_b64_e32 v[34:35], v[50:51]
	v_mov_b64_e32 v[36:37], v[52:53]
	v_mov_b64_e32 v[38:39], v[54:55]
	v_mov_b64_e32 v[40:41], v[56:57]
	v_mov_b64_e32 v[42:43], v[58:59]
	v_mov_b64_e32 v[44:45], v[60:61]
	v_mov_b64_e32 v[46:47], v[62:63]
	v_mov_b64_e32 v[48:49], v[64:65]
	v_mov_b32_e32 v114, v214
	s_mov_b32 s11, s68
	v_lshl_add_u32 v50, v204, 4, s88
	s_branch .LBB0_565
